# mini GEMMs: all A-fragment loads then all B-fragment loads (P8 sample-row tail 14 -> 10.7 us by probe), fix-up items keep the 4-k-step line groups
# baseline (speedup 1.0000x reference)
; __device__ __forceinline__ unsigned f2bf(float f) { unsigned u = __float_as_uint(f); return (u + 0x7fffu + ((u >> 16) & 1u)) >> 16; }
; template <int MODE>
; __device__ __forceinline__ void mini_gemm(LAS unsigned char* lds, const bf16_t* A, const bf16_t* Bt, int K, int N, bf16_t* O, int ldc, const float* rstd, float* sumsq, int bx, int G, int tid, int wave, int lane) {
;     ...
;     for (int tile = bx; tile < ntiles; tile += G) {
;         const int m0 = (tile / ntn) * 32, n0 = (tile % ntn) * 32;
;         const bf16_t* ap = A + (size_t)(m0 + r) * K + wave * kw + 8 * hf; const bf16_t* bp = Bt + (size_t)(n0 + r) * K + wave * kw + 8 * hf;
;         f32x16 acc; for (int i = 0; i < 16; ++i) acc[i] = 0.f;
;         for (int k = 0; k < kw; k += 16) { const bf16x8 af = *(const bf16x8*)(ap + k), bf = *(const bf16x8*)(bp + k); acc = __builtin_amdgcn_mfma_f32_32x32x16_bf16(af, bf, acc, 0, 0, 0); }
;         __syncthreads();
; #pragma unroll
;         for (int i = 0; i < 16; ++i) red[(wave * 16 + i) * 64 + lane] = acc[i];
;         __syncthreads();
; #pragma unroll
;         for (int h2 = 0; h2 < 2; ++h2) {
;             const int e = tid + h2 * 512, i = e >> 6, ln = e & 63;
;             float v = 0.f;
; #pragma unroll
;             for (int w = 0; w < 8; ++w) v += red[(w * 16 + i) * 64 + ln];
;             const int row = m0 + (i & 3) + 8 * (i >> 2) + 4 * (ln >> 5), col = n0 + (ln & 31);
;             if (MODE == 0) { O[(size_t)row * ldc + col] = (bf16_t)f2bf(v * rstd[row]); }
.LBB0_169:
	s_ashr_i32 s11, s10, 31
	s_lshr_b32 s11, s11, 26
	s_add_i32 s11, s10, s11
	s_ashr_i32 s11, s11, 6
	s_lshl_b32 s12, s11, 5
	s_lshl_b32 s11, s11, 11
	v_or_b32_e32 v0, s12, v20
	v_subrev_u32_e32 v48, s11, v26
	v_ashrrev_i32_e32 v1, 31, v0
	v_ashrrev_i32_e32 v49, 31, v48
	v_lshlrev_b64 v[0:1], 11, v[0:1]
	v_lshlrev_b64 v[2:3], 11, v[48:49]
	v_lshl_add_u64 v[50:51], v[16:17], 0, v[0:1]
	v_lshl_add_u64 v[52:53], v[18:19], 0, v[2:3]
	s_add_i32 s10, s10, s38
	v_add_u32_e32 v26, s8, v26
	s_cmpk_lt_i32 s10, 0x200
	v_or_b32_e32 v41, s12, v21
	v_or_b32_e32 v40, v41, v23
	v_add_u32_e32 v42, v41, v25
	v_ashrrev_i32_e32 v41, 31, v40
	v_ashrrev_i32_e32 v43, 31, v42
	v_lshl_add_u64 v[32:33], v[40:41], 2, s[6:7]
	v_lshl_add_u64 v[34:35], v[42:43], 2, s[6:7]
	global_load_dwordx4 v[100:103], v[50:51], off
	global_load_dwordx4 v[104:107], v[50:51], off offset:32
	global_load_dwordx4 v[108:111], v[50:51], off offset:64
	global_load_dwordx4 v[112:115], v[50:51], off offset:96
	global_load_dwordx4 v[116:119], v[50:51], off offset:128
	global_load_dwordx4 v[120:123], v[50:51], off offset:160
	global_load_dwordx4 v[124:127], v[50:51], off offset:192
	global_load_dwordx4 v[128:131], v[50:51], off offset:224
	global_load_dwordx4 v[132:135], v[52:53], off
	global_load_dwordx4 v[136:139], v[52:53], off offset:32
	global_load_dwordx4 v[140:143], v[52:53], off offset:64
	global_load_dwordx4 v[144:147], v[52:53], off offset:96
	global_load_dwordx4 v[148:151], v[52:53], off offset:128
	global_load_dwordx4 v[152:155], v[52:53], off offset:160
	global_load_dwordx4 v[156:159], v[52:53], off offset:192
	global_load_dwordx4 v[160:163], v[52:53], off offset:224
	s_waitcnt vmcnt(7)
	v_mfma_f32_32x32x16_bf16 v[0:15], v[100:103], v[132:135], 0
	s_waitcnt vmcnt(6)
	v_mfma_f32_32x32x16_bf16 v[0:15], v[104:107], v[136:139], v[0:15]
	s_waitcnt vmcnt(5)
	v_mfma_f32_32x32x16_bf16 v[0:15], v[108:111], v[140:143], v[0:15]
	s_waitcnt vmcnt(4)
	v_mfma_f32_32x32x16_bf16 v[0:15], v[112:115], v[144:147], v[0:15]
	s_waitcnt vmcnt(3)
	v_mfma_f32_32x32x16_bf16 v[0:15], v[116:119], v[148:151], v[0:15]
	s_waitcnt vmcnt(2)
	v_mfma_f32_32x32x16_bf16 v[0:15], v[120:123], v[152:155], v[0:15]
	s_barrier
	s_waitcnt vmcnt(1)
	v_mfma_f32_32x32x16_bf16 v[0:15], v[124:127], v[156:159], v[0:15]
	s_waitcnt vmcnt(0)
	v_mfma_f32_32x32x16_bf16 v[0:15], v[128:131], v[160:163], v[0:15]
	s_nop 11
	ds_write2st64_b32 v27, v0, v1 offset1:1
	ds_write2st64_b32 v27, v2, v3 offset0:2 offset1:3
	ds_write2st64_b32 v27, v4, v5 offset0:4 offset1:5
	ds_write2st64_b32 v27, v6, v7 offset0:6 offset1:7
	ds_write2st64_b32 v27, v8, v9 offset0:8 offset1:9
	ds_write2st64_b32 v27, v10, v11 offset0:10 offset1:11
	ds_write2st64_b32 v27, v12, v13 offset0:12 offset1:13
	ds_write2st64_b32 v27, v14, v15 offset0:14 offset1:15
	s_waitcnt lgkmcnt(0)
	s_barrier
	global_load_dword v32, v[32:33], off
	s_nop 0
	global_load_dword v33, v[34:35], off
	v_lshl_add_u64 v[0:1], v[48:49], 1, s[2:3]
	v_lshlrev_b64 v[2:3], 12, v[40:41]
	v_lshlrev_b64 v[4:5], 12, v[42:43]
	v_lshl_add_u64 v[2:3], v[0:1], 0, v[2:3]
	v_lshl_add_u64 v[0:1], v[0:1], 0, v[4:5]
	ds_read2st64_b32 v[4:5], v22 offset1:16
	ds_read2st64_b32 v[6:7], v22 offset0:32 offset1:48
	ds_read2st64_b32 v[8:9], v22 offset0:64 offset1:80
	ds_read2st64_b32 v[10:11], v22 offset0:96 offset1:112
	ds_read2st64_b32 v[12:13], v24 offset1:16
	ds_read2st64_b32 v[14:15], v24 offset0:32 offset1:48
	ds_read2st64_b32 v[28:29], v24 offset0:64 offset1:80
	ds_read2st64_b32 v[30:31], v24 offset0:96 offset1:112
	s_waitcnt lgkmcnt(7)
	v_add_f32_e32 v4, 0, v4
	s_waitcnt lgkmcnt(3)
	v_add_f32_e32 v12, 0, v12
	v_add_f32_e32 v4, v4, v5
	v_add_f32_e32 v5, v12, v13
	v_add_f32_e32 v4, v4, v6
	s_waitcnt lgkmcnt(2)
	v_add_f32_e32 v5, v5, v14
	v_add_f32_e32 v4, v4, v7
	v_add_f32_e32 v5, v5, v15
	v_add_f32_e32 v4, v4, v8
	s_waitcnt lgkmcnt(1)
	v_add_f32_e32 v5, v5, v28
	v_add_f32_e32 v4, v4, v9
	v_add_f32_e32 v5, v5, v29
	v_add_f32_e32 v4, v4, v10
	s_waitcnt lgkmcnt(0)
	v_add_f32_e32 v5, v5, v30
	v_add_f32_e32 v4, v4, v11
	v_add_f32_e32 v5, v5, v31
	s_waitcnt vmcnt(1)
	v_mul_f32_e32 v4, v4, v32
	s_waitcnt vmcnt(0)
	v_mul_f32_e32 v5, v5, v33
	v_bfe_u32 v6, v4, 16, 1
	v_bfe_u32 v7, v5, 16, 1
	v_add3_u32 v4, v4, v6, s9
	v_add3_u32 v5, v5, v7, s9
	global_store_short_d16_hi v[2:3], v4, off
	global_store_short_d16_hi v[0:1], v5, off
	s_cbranch_scc1 .LBB0_169

; __device__ __forceinline__ unsigned f2bf(float f) { unsigned u = __float_as_uint(f); return (u + 0x7fffu + ((u >> 16) & 1u)) >> 16; }
; template <int MODE>
; __device__ __forceinline__ void mini_gemm(LAS unsigned char* lds, const bf16_t* A, const bf16_t* Bt, int K, int N, bf16_t* O, int ldc, const float* rstd, float* sumsq, int bx, int G, int tid, int wave, int lane) {
;     ...
;     for (int tile = bx; tile < ntiles; tile += G) {
;         const int m0 = (tile / ntn) * 32, n0 = (tile % ntn) * 32;
;         const bf16_t* ap = A + (size_t)(m0 + r) * K + wave * kw + 8 * hf; const bf16_t* bp = Bt + (size_t)(n0 + r) * K + wave * kw + 8 * hf;
;         f32x16 acc; for (int i = 0; i < 16; ++i) acc[i] = 0.f;
;         for (int k = 0; k < kw; k += 16) { const bf16x8 af = *(const bf16x8*)(ap + k), bf = *(const bf16x8*)(bp + k); acc = __builtin_amdgcn_mfma_f32_32x32x16_bf16(af, bf, acc, 0, 0, 0); }
;         __syncthreads();
; #pragma unroll
;         for (int i = 0; i < 16; ++i) red[(wave * 16 + i) * 64 + lane] = acc[i];
;         __syncthreads();
; #pragma unroll
;         for (int h2 = 0; h2 < 2; ++h2) {
;             const int e = tid + h2 * 512, i = e >> 6, ln = e & 63;
;             float v = 0.f;
; #pragma unroll
;             for (int w = 0; w < 8; ++w) v += red[(w * 16 + i) * 64 + ln];
;             const int row = m0 + (i & 3) + 8 * (i >> 2) + 4 * (ln >> 5), col = n0 + (ln & 31);
;             if (MODE == 0) { O[(size_t)row * ldc + col] = (bf16_t)f2bf(v * rstd[row]); }
;             else { O[(size_t)row * ldc + col] = (bf16_t)f2bf(v); float ss = v * v;
; #pragma unroll
;                 for (int o = 1; o < 32; o <<= 1) ss += __shfl_xor(ss, o);
;                 if ((ln & 31) == 0) atomicAdd(sumsq + row, ss); }
.LBB0_990:
	s_ashr_i32 s0, s10, 31
	s_lshr_b32 s0, s0, 27
	s_add_i32 s0, s10, s0
	s_and_b32 s1, s0, 0xffffffe0
	v_or_b32_e32 v0, s1, v20
	v_ashrrev_i32_e32 v1, 31, v0
	v_lshlrev_b64 v[0:1], 11, v[0:1]
	v_lshl_add_u64 v[56:57], v[16:17], 0, v[0:1]
	s_lshl_b32 s0, s0, 5
	s_and_b32 s0, s0, 0xfffffc00
	v_subrev_u32_e32 v54, s0, v31
	v_ashrrev_i32_e32 v55, 31, v54
	s_waitcnt lgkmcnt(0)
	v_lshlrev_b64 v[4:5], 11, v[54:55]
	v_lshl_add_u64 v[58:59], v[18:19], 0, v[4:5]
	global_load_dwordx4 v[100:103], v[56:57], off
	global_load_dwordx4 v[104:107], v[56:57], off offset:32
	global_load_dwordx4 v[108:111], v[56:57], off offset:64
	global_load_dwordx4 v[112:115], v[56:57], off offset:96
	global_load_dwordx4 v[116:119], v[56:57], off offset:128
	global_load_dwordx4 v[120:123], v[56:57], off offset:160
	global_load_dwordx4 v[124:127], v[56:57], off offset:192
	global_load_dwordx4 v[128:131], v[56:57], off offset:224
	global_load_dwordx4 v[132:135], v[58:59], off
	global_load_dwordx4 v[136:139], v[58:59], off offset:32
	global_load_dwordx4 v[140:143], v[58:59], off offset:64
	global_load_dwordx4 v[144:147], v[58:59], off offset:96
	global_load_dwordx4 v[148:151], v[58:59], off offset:128
	global_load_dwordx4 v[152:155], v[58:59], off offset:160
	global_load_dwordx4 v[156:159], v[58:59], off offset:192
	global_load_dwordx4 v[160:163], v[58:59], off offset:224
	s_waitcnt vmcnt(7)
	v_mfma_f32_32x32x16_bf16 v[0:15], v[100:103], v[132:135], 0
	s_waitcnt vmcnt(6)
	v_mfma_f32_32x32x16_bf16 v[0:15], v[104:107], v[136:139], v[0:15]
	s_waitcnt vmcnt(5)
	v_mfma_f32_32x32x16_bf16 v[0:15], v[108:111], v[140:143], v[0:15]
	s_waitcnt vmcnt(4)
	v_mfma_f32_32x32x16_bf16 v[0:15], v[112:115], v[144:147], v[0:15]
	s_waitcnt vmcnt(3)
	v_mfma_f32_32x32x16_bf16 v[0:15], v[116:119], v[148:151], v[0:15]
	s_waitcnt vmcnt(2)
	v_mfma_f32_32x32x16_bf16 v[0:15], v[120:123], v[152:155], v[0:15]
	s_barrier
	s_waitcnt vmcnt(1)
	v_mfma_f32_32x32x16_bf16 v[0:15], v[124:127], v[156:159], v[0:15]
	s_waitcnt vmcnt(0)
	v_mfma_f32_32x32x16_bf16 v[0:15], v[128:131], v[160:163], v[0:15]
	s_nop 11
	ds_write2st64_b32 v32, v0, v1 offset1:1
	ds_write2st64_b32 v32, v2, v3 offset0:2 offset1:3
	ds_write2st64_b32 v32, v4, v5 offset0:4 offset1:5
	ds_write2st64_b32 v32, v6, v7 offset0:6 offset1:7
	ds_write2st64_b32 v32, v8, v9 offset0:8 offset1:9
	ds_write2st64_b32 v32, v10, v11 offset0:10 offset1:11
	ds_write2st64_b32 v32, v12, v13 offset0:12 offset1:13
	ds_write2st64_b32 v32, v14, v15 offset0:14 offset1:15
	s_waitcnt lgkmcnt(0)
	s_barrier
	ds_read2st64_b32 v[0:1], v22 offset1:16
	ds_read2st64_b32 v[2:3], v22 offset0:32 offset1:48
	ds_read2st64_b32 v[4:5], v22 offset0:64 offset1:80
	s_waitcnt lgkmcnt(2)
	v_add_f32_e32 v0, 0, v0
	v_add_f32_e32 v6, v0, v1
	ds_read2st64_b32 v[0:1], v22 offset0:96 offset1:112
	s_waitcnt lgkmcnt(2)
	v_add_f32_e32 v2, v6, v2
	v_add_f32_e32 v2, v2, v3
	s_waitcnt lgkmcnt(1)
	v_add_f32_e32 v2, v2, v4
	v_add_f32_e32 v2, v2, v5
	s_waitcnt lgkmcnt(0)
	v_add_f32_e32 v0, v2, v0
	v_add_f32_e32 v3, v0, v1
	v_mul_f32_e32 v0, v3, v3
	ds_bpermute_b32 v0, v24, v0
	v_or_b32_e32 v4, s1, v21
	v_or_b32_e32 v2, v4, v23
	v_bfe_u32 v7, v3, 16, 1
	v_add3_u32 v7, v3, v7, s9
	s_waitcnt lgkmcnt(0)
	v_fmac_f32_e32 v0, v3, v3
	ds_bpermute_b32 v1, v25, v0
	v_ashrrev_i32_e32 v3, 31, v2
	v_lshlrev_b64 v[8:9], 11, v[2:3]
	s_waitcnt lgkmcnt(0)
	v_add_f32_e32 v0, v0, v1
	ds_bpermute_b32 v1, v26, v0
	s_waitcnt lgkmcnt(0)
	v_add_f32_e32 v5, v0, v1
	ds_bpermute_b32 v6, v27, v5
	v_lshl_add_u64 v[0:1], v[54:55], 1, s[2:3]
	v_lshl_add_u64 v[8:9], v[0:1], 0, v[8:9]
	global_store_short_d16_hi v[8:9], v7, off
	s_waitcnt lgkmcnt(0)
	v_add_f32_e32 v5, v5, v6
	ds_bpermute_b32 v6, v28, v5
	s_and_saveexec_b64 s[0:1], vcc
	s_cbranch_execz .LBB0_992
	v_lshl_add_u64 v[2:3], v[2:3], 2, s[6:7]
	s_waitcnt lgkmcnt(0)
	v_add_f32_e32 v5, v5, v6
	global_atomic_add_f32 v[2:3], v5, off

; #define LAS __attribute__((address_space(3)))
; __device__ __forceinline__ unsigned f2bf(float f) { unsigned u = __float_as_uint(f); return (u + 0x7fffu + ((u >> 16) & 1u)) >> 16; }
; template <int MODE>
; __device__ __forceinline__ void mini_gemm(LAS unsigned char* lds, const bf16_t* A, const bf16_t* Bt, int K, int N, bf16_t* O, int ldc, const float* rstd, float* sumsq, int bx, int G, int tid, int wave, int lane) {
;     const int r = lane & 31, hf = lane >> 5, ntn = N >> 5, ntiles = 8 * ntn, kw = K >> 3;
;     LAS float* red = (LAS float*)lds;
;     for (int tile = bx; tile < ntiles; tile += G) {
;         const int m0 = (tile / ntn) * 32, n0 = (tile % ntn) * 32;
;         const bf16_t* ap = A + (size_t)(m0 + r) * K + wave * kw + 8 * hf; const bf16_t* bp = Bt + (size_t)(n0 + r) * K + wave * kw + 8 * hf;
;         f32x16 acc; for (int i = 0; i < 16; ++i) acc[i] = 0.f;
;         for (int k = 0; k < kw; k += 16) { const bf16x8 af = *(const bf16x8*)(ap + k), bf = *(const bf16x8*)(bp + k); acc = __builtin_amdgcn_mfma_f32_32x32x16_bf16(af, bf, acc, 0, 0, 0); }
;         __syncthreads();
; #pragma unroll
;         for (int i = 0; i < 16; ++i) red[(wave * 16 + i) * 64 + lane] = acc[i];
;         __syncthreads();
; #pragma unroll
;         for (int h2 = 0; h2 < 2; ++h2) {
;             const int e = tid + h2 * 512, i = e >> 6, ln = e & 63;
;             float v = 0.f;
; #pragma unroll
;             for (int w = 0; w < 8; ++w) v += red[(w * 16 + i) * 64 + ln];
;             const int row = m0 + (i & 3) + 8 * (i >> 2) + 4 * (ln >> 5), col = n0 + (ln & 31);
;             if (MODE == 0) { O[(size_t)row * ldc + col] = (bf16_t)f2bf(v * rstd[row]); }
;             else { O[(size_t)row * ldc + col] = (bf16_t)f2bf(v); float ss = v * v;
; #pragma unroll
;                 for (int o = 1; o < 32; o <<= 1) ss += __shfl_xor(ss, o);
;                 if ((ln & 31) == 0) atomicAdd(sumsq + row, ss); }
.LBB0_1296:
	s_ashr_i32 s0, s96, 31
	s_lshr_b32 s0, s0, 27
	s_add_i32 s0, s96, s0
	s_and_b32 s13, s0, 0xffffffe0
	v_or_b32_e32 v0, s13, v20
	s_ashr_i32 s12, s0, 5
	v_mad_i64_i32 v[54:55], s[0:1], v0, s10, v[16:17]
	s_mul_i32 s14, s12, 0xffd40000
	v_add_u32_e32 v4, s14, v32
	s_waitcnt lgkmcnt(0)
	v_ashrrev_i32_e32 v5, 31, v4
	v_lshl_add_u64 v[56:57], v[4:5], 1, v[18:19]
	s_lshl_b32 s0, s12, 10
	global_load_dwordx4 v[60:63], v[54:55], off
	global_load_dwordx4 v[64:67], v[54:55], off offset:32
	global_load_dwordx4 v[68:71], v[54:55], off offset:64
	global_load_dwordx4 v[72:75], v[54:55], off offset:96
	global_load_dwordx4 v[76:79], v[54:55], off offset:128
	global_load_dwordx4 v[80:83], v[54:55], off offset:160
	global_load_dwordx4 v[84:87], v[54:55], off offset:192
	global_load_dwordx4 v[88:91], v[54:55], off offset:224
	global_load_dwordx4 v[92:95], v[54:55], off offset:256
	global_load_dwordx4 v[96:99], v[54:55], off offset:288
	global_load_dwordx4 v[100:103], v[54:55], off offset:320
	global_load_dwordx4 v[104:107], v[54:55], off offset:352
	global_load_dwordx4 v[108:111], v[54:55], off offset:384
	global_load_dwordx4 v[112:115], v[54:55], off offset:416
	global_load_dwordx4 v[116:119], v[54:55], off offset:448
	global_load_dwordx4 v[120:123], v[54:55], off offset:480
	global_load_dwordx4 v[124:127], v[54:55], off offset:512
	global_load_dwordx4 v[128:131], v[54:55], off offset:544
	global_load_dwordx4 v[132:135], v[54:55], off offset:576
	global_load_dwordx4 v[136:139], v[54:55], off offset:608
	global_load_dwordx4 v[140:143], v[54:55], off offset:640
	global_load_dwordx4 v[144:147], v[54:55], off offset:672
	global_load_dwordx4 v[148:151], v[56:57], off
	global_load_dwordx4 v[152:155], v[56:57], off offset:32
	global_load_dwordx4 v[156:159], v[56:57], off offset:64
	global_load_dwordx4 v[160:163], v[56:57], off offset:96
	global_load_dwordx4 v[164:167], v[56:57], off offset:128
	global_load_dwordx4 v[168:171], v[56:57], off offset:160
	global_load_dwordx4 v[180:183], v[56:57], off offset:192
	global_load_dwordx4 v[184:187], v[56:57], off offset:224
	global_load_dwordx4 v[188:191], v[56:57], off offset:256
	global_load_dwordx4 v[192:195], v[56:57], off offset:288
	global_load_dwordx4 v[196:199], v[56:57], off offset:320
	global_load_dwordx4 v[200:203], v[56:57], off offset:352
	global_load_dwordx4 v[204:207], v[56:57], off offset:384
	global_load_dwordx4 v[208:211], v[56:57], off offset:416
	global_load_dwordx4 v[212:215], v[56:57], off offset:448
	global_load_dwordx4 v[216:219], v[56:57], off offset:480
	global_load_dwordx4 v[220:223], v[56:57], off offset:512
	global_load_dwordx4 v[224:227], v[56:57], off offset:544
	global_load_dwordx4 v[228:231], v[56:57], off offset:576
	global_load_dwordx4 v[232:235], v[56:57], off offset:608
	global_load_dwordx4 v[236:239], v[56:57], off offset:640
	global_load_dwordx4 v[240:243], v[56:57], off offset:672
	s_waitcnt vmcnt(21)
	v_mfma_f32_32x32x16_bf16 v[0:15], v[60:63], v[148:151], 0
	s_waitcnt vmcnt(20)
	v_mfma_f32_32x32x16_bf16 v[0:15], v[64:67], v[152:155], v[0:15]
	s_waitcnt vmcnt(19)
	v_mfma_f32_32x32x16_bf16 v[0:15], v[68:71], v[156:159], v[0:15]
	s_waitcnt vmcnt(18)
	v_mfma_f32_32x32x16_bf16 v[0:15], v[72:75], v[160:163], v[0:15]
	s_waitcnt vmcnt(17)
	v_mfma_f32_32x32x16_bf16 v[0:15], v[76:79], v[164:167], v[0:15]
	s_waitcnt vmcnt(16)
	v_mfma_f32_32x32x16_bf16 v[0:15], v[80:83], v[168:171], v[0:15]
	s_waitcnt vmcnt(15)
	v_mfma_f32_32x32x16_bf16 v[0:15], v[84:87], v[180:183], v[0:15]
	s_waitcnt vmcnt(14)
	v_mfma_f32_32x32x16_bf16 v[0:15], v[88:91], v[184:187], v[0:15]
	s_waitcnt vmcnt(13)
	v_mfma_f32_32x32x16_bf16 v[0:15], v[92:95], v[188:191], v[0:15]
	s_waitcnt vmcnt(12)
	v_mfma_f32_32x32x16_bf16 v[0:15], v[96:99], v[192:195], v[0:15]
	s_waitcnt vmcnt(11)
	v_mfma_f32_32x32x16_bf16 v[0:15], v[100:103], v[196:199], v[0:15]
	s_waitcnt vmcnt(10)
	v_mfma_f32_32x32x16_bf16 v[0:15], v[104:107], v[200:203], v[0:15]
	s_waitcnt vmcnt(9)
	v_mfma_f32_32x32x16_bf16 v[0:15], v[108:111], v[204:207], v[0:15]
	s_waitcnt vmcnt(8)
	v_mfma_f32_32x32x16_bf16 v[0:15], v[112:115], v[208:211], v[0:15]
	s_waitcnt vmcnt(7)
	v_mfma_f32_32x32x16_bf16 v[0:15], v[116:119], v[212:215], v[0:15]
	s_waitcnt vmcnt(6)
	v_mfma_f32_32x32x16_bf16 v[0:15], v[120:123], v[216:219], v[0:15]
	s_waitcnt vmcnt(5)
	v_mfma_f32_32x32x16_bf16 v[0:15], v[124:127], v[220:223], v[0:15]
	s_waitcnt vmcnt(4)
	v_mfma_f32_32x32x16_bf16 v[0:15], v[128:131], v[224:227], v[0:15]
	s_waitcnt vmcnt(3)
	v_mfma_f32_32x32x16_bf16 v[0:15], v[132:135], v[228:231], v[0:15]
	s_waitcnt vmcnt(2)
	v_mfma_f32_32x32x16_bf16 v[0:15], v[136:139], v[232:235], v[0:15]
	s_barrier
	s_waitcnt vmcnt(1)
	v_mfma_f32_32x32x16_bf16 v[0:15], v[140:143], v[236:239], v[0:15]
	s_waitcnt vmcnt(0)
	v_mfma_f32_32x32x16_bf16 v[0:15], v[144:147], v[240:243], v[0:15]
	s_nop 11
	ds_write2st64_b32 v33, v0, v1 offset1:1
	ds_write2st64_b32 v33, v2, v3 offset0:2 offset1:3
	ds_write2st64_b32 v33, v4, v5 offset0:4 offset1:5
	ds_write2st64_b32 v33, v6, v7 offset0:6 offset1:7
	ds_write2st64_b32 v33, v8, v9 offset0:8 offset1:9
	ds_write2st64_b32 v33, v10, v11 offset0:10 offset1:11
	ds_write2st64_b32 v33, v12, v13 offset0:12 offset1:13
	ds_write2st64_b32 v33, v14, v15 offset0:14 offset1:15
	s_waitcnt lgkmcnt(0)
	s_barrier
	ds_read2st64_b32 v[0:1], v22 offset1:16
	ds_read2st64_b32 v[2:3], v22 offset0:32 offset1:48
	ds_read2st64_b32 v[4:5], v22 offset0:64 offset1:80
	s_waitcnt lgkmcnt(2)
	v_add_f32_e32 v0, 0, v0
	v_add_f32_e32 v6, v0, v1
	ds_read2st64_b32 v[0:1], v22 offset0:96 offset1:112
	s_waitcnt lgkmcnt(2)
	v_add_f32_e32 v2, v6, v2
	v_add_f32_e32 v2, v2, v3
	s_waitcnt lgkmcnt(1)
	v_add_f32_e32 v2, v2, v4
	v_add_f32_e32 v2, v2, v5
	s_waitcnt lgkmcnt(0)
	v_add_f32_e32 v0, v2, v0
	v_add_f32_e32 v3, v0, v1
	v_mul_f32_e32 v0, v3, v3
	ds_bpermute_b32 v0, v24, v0
	v_or_b32_e32 v4, s13, v21
	v_bfe_u32 v7, v3, 16, 1
	v_add3_u32 v7, v3, v7, s11
	s_waitcnt lgkmcnt(0)
	v_fmac_f32_e32 v0, v3, v3
	ds_bpermute_b32 v1, v25, v0
	s_waitcnt lgkmcnt(0)
	v_add_f32_e32 v2, v0, v1
	ds_bpermute_b32 v5, v26, v2
	v_subrev_u32_e32 v0, s0, v31
	v_ashrrev_i32_e32 v1, 31, v0
	v_lshl_add_u64 v[0:1], v[0:1], 1, s[2:3]
	s_waitcnt lgkmcnt(0)
	v_add_f32_e32 v5, v2, v5
	ds_bpermute_b32 v6, v27, v5
	v_or_b32_e32 v2, v4, v23
	v_ashrrev_i32_e32 v3, 31, v2
	v_lshlrev_b64 v[8:9], 11, v[2:3]
	v_lshl_add_u64 v[8:9], v[0:1], 0, v[8:9]
	s_waitcnt lgkmcnt(0)
	v_add_f32_e32 v5, v5, v6
	ds_bpermute_b32 v6, v28, v5
	global_store_short_d16_hi v[8:9], v7, off
	s_and_saveexec_b64 s[0:1], vcc
	s_cbranch_execz .LBB0_1298
	v_lshl_add_u64 v[2:3], v[2:3], 2, s[4:5]
	s_waitcnt lgkmcnt(0)
	v_add_f32_e32 v5, v5, v6
	global_atomic_add_f32 v[2:3], v5, off
